# A/B of the static priority: raise waves 0-3 (tid<256) instead of waves 4-7, everything else as previous
# speedup vs baseline: 1.0363x; 1.0097x over previous
.LBB0_24:
	v_readlane_b32 s48, v253, 16
	s_mov_b64 s[82:83], 0x60000
	s_movk_i32 s90, 0x104
	v_readfirstlane_b32 s2, v193
	s_nop 1
	s_cmpk_gt_u32 s2, 0xff
	s_cbranch_scc1 .Lprio_skip
	s_setprio 1
